# v83 + hand-scheduled SwiGLU epilogue (8 elements per store evaluated together with packed f32 mul/add, addresses up front; same per-element operation order)
# speedup vs baseline: 1.0076x; 1.0015x over previous
; __device__ __forceinline__ unsigned cvt_pk_bf16(float lo, float hi) { unsigned r; asm volatile("v_cvt_pk_bf16_f32 %0, %1, %2" : "=v"(r) : "v"(lo), "v"(hi)); return r; }
; __device__ __forceinline__ float siluf_(float x) { return x * __builtin_amdgcn_rcpf(1.0f + __expf(-x)); }
;     __device__ __forceinline__ void operator()(const f32x4 (&acc)[2][2][4][2], const Unit& u, int wr, int wc, int fr, int fq) const {
;         const int row0 = u.pm * BM + wr * 64 + fr, col0 = u.pn * 128 + wc * 32 + 8 * fq;
; #pragma unroll
;         for (int ai = 0; ai < 2; ++ai)
; #pragma unroll
;             for (int m = 0; m < 4; ++m) { bf16_t* rowp = O + (size_t)(row0 + ai * HALF + m * 16) * DFF + col0;
;                 float r[8];
; #pragma unroll
;                 for (int n = 0; n < 2; ++n)
; #pragma unroll
;                     for (int j = 0; j < 4; ++j) r[n * 4 + j] = siluf_(acc[ai][0][m][n][j]) * acc[ai][1][m][n][j];
;                 u32x4 w; w.x = cvt_pk_bf16(r[0], r[1]); w.y = cvt_pk_bf16(r[2], r[3]); w.z = cvt_pk_bf16(r[4], r[5]); w.w = cvt_pk_bf16(r[6], r[7]);
;                 *(u32x4*)rowp = w; }
.LBB0_205:
	v_mov_b32_e32 v150, v142
	s_lshl_b32 s18, s56, 8
	s_add_i32 s18, s18, s47
	v_and_or_b32 v151, v150, 15, s18
	s_lshl_b32 s18, s78, 7
	s_or_b32 s18, s18, s57
	v_ashrrev_i32_e32 v150, 1, v150
	v_and_b32_e32 v150, -8, v150
	v_add_u32_e32 v152, s18, v150
	v_readlane_b32 s18, v255, 24
	v_readlane_b32 s19, v255, 25
	v_ashrrev_i32_e32 v153, 31, v152
	s_movk_i32 s27, 0x1600
	s_mov_b32 s100, 0xbfb8aa3b
	v_lshlrev_b64 v[154:155], 1, v[152:153]
	v_mov_b64_e32 v[156:157], s[18:19]
	v_mad_i64_i32 v[160:161], s[18:19], v151, s27, v[156:157]
	v_lshl_add_u64 v[160:161], v[160:161], 0, v[154:155]
	v_add_u32_e32 v158, 0x10, v151
	v_mad_i64_i32 v[162:163], s[18:19], v158, s27, v[156:157]
	v_lshl_add_u64 v[162:163], v[162:163], 0, v[154:155]
	v_add_u32_e32 v158, 0x20, v151
	v_mad_i64_i32 v[164:165], s[18:19], v158, s27, v[156:157]
	v_lshl_add_u64 v[164:165], v[164:165], 0, v[154:155]
	v_add_u32_e32 v158, 0x30, v151
	v_mad_i64_i32 v[176:177], s[18:19], v158, s27, v[156:157]
	v_lshl_add_u64 v[176:177], v[176:177], 0, v[154:155]
	v_add_u32_e32 v158, 0x80, v151
	v_mad_i64_i32 v[178:179], s[18:19], v158, s27, v[156:157]
	v_lshl_add_u64 v[178:179], v[178:179], 0, v[154:155]
	v_add_u32_e32 v158, 0x90, v151
	v_mad_i64_i32 v[180:181], s[18:19], v158, s27, v[156:157]
	v_lshl_add_u64 v[180:181], v[180:181], 0, v[154:155]
	v_add_u32_e32 v158, 0xa0, v151
	v_mad_i64_i32 v[182:183], s[18:19], v158, s27, v[156:157]
	v_lshl_add_u64 v[182:183], v[182:183], 0, v[154:155]
	v_add_u32_e32 v158, 0xb0, v151
	v_mad_i64_i32 v[184:185], s[18:19], v158, s27, v[156:157]
	v_lshl_add_u64 v[184:185], v[184:185], 0, v[154:155]
	s_nop 1
	s_mov_b64 s[18:19], -1
	v_pk_mul_f32 v[188:189], v[126:127], s[100:101] op_sel_hi:[1,0]
	v_pk_mul_f32 v[190:191], v[128:129], s[100:101] op_sel_hi:[1,0]
	v_pk_mul_f32 v[192:193], v[118:119], s[100:101] op_sel_hi:[1,0]
	v_pk_mul_f32 v[194:195], v[120:121], s[100:101] op_sel_hi:[1,0]
	v_exp_f32_e32 v188, v188
	v_exp_f32_e32 v189, v189
	v_exp_f32_e32 v190, v190
	v_exp_f32_e32 v191, v191
	v_exp_f32_e32 v192, v192
	v_exp_f32_e32 v193, v193
	v_exp_f32_e32 v194, v194
	v_exp_f32_e32 v195, v195
	v_pk_mul_f32 v[204:205], v[110:111], s[100:101] op_sel_hi:[1,0]
	v_pk_mul_f32 v[206:207], v[112:113], s[100:101] op_sel_hi:[1,0]
	v_pk_mul_f32 v[208:209], v[102:103], s[100:101] op_sel_hi:[1,0]
	v_pk_mul_f32 v[210:211], v[104:105], s[100:101] op_sel_hi:[1,0]
	v_exp_f32_e32 v204, v204
	v_exp_f32_e32 v205, v205
	v_exp_f32_e32 v206, v206
	v_exp_f32_e32 v207, v207
	v_exp_f32_e32 v208, v208
	v_exp_f32_e32 v209, v209
	v_exp_f32_e32 v210, v210
	v_exp_f32_e32 v211, v211
	v_pk_add_f32 v[188:189], v[188:189], 1.0 op_sel_hi:[1,0]
	v_pk_add_f32 v[190:191], v[190:191], 1.0 op_sel_hi:[1,0]
	v_pk_add_f32 v[192:193], v[192:193], 1.0 op_sel_hi:[1,0]
	v_pk_add_f32 v[194:195], v[194:195], 1.0 op_sel_hi:[1,0]
	v_rcp_f32_e32 v188, v188
	v_rcp_f32_e32 v189, v189
	v_rcp_f32_e32 v190, v190
	v_rcp_f32_e32 v191, v191
	v_rcp_f32_e32 v192, v192
	v_rcp_f32_e32 v193, v193
	v_rcp_f32_e32 v194, v194
	v_rcp_f32_e32 v195, v195
	v_pk_mul_f32 v[188:189], v[126:127], v[188:189]
	v_pk_mul_f32 v[190:191], v[128:129], v[190:191]
	v_pk_mul_f32 v[192:193], v[118:119], v[192:193]
	v_pk_mul_f32 v[194:195], v[120:121], v[194:195]
	v_pk_mul_f32 v[122:123], v[122:123], v[188:189]
	v_pk_mul_f32 v[124:125], v[124:125], v[190:191]
	v_pk_mul_f32 v[114:115], v[114:115], v[192:193]
	v_pk_mul_f32 v[116:117], v[116:117], v[194:195]
	v_cvt_pk_bf16_f32 v196, v122, v123
	v_cvt_pk_bf16_f32 v197, v124, v125
	v_cvt_pk_bf16_f32 v198, v114, v115
	v_cvt_pk_bf16_f32 v199, v116, v117
	global_store_dwordx4 v[160:161], v[196:199], off sc1
	v_pk_mul_f32 v[188:189], v[94:95], s[100:101] op_sel_hi:[1,0]
	v_pk_mul_f32 v[190:191], v[96:97], s[100:101] op_sel_hi:[1,0]
	v_pk_mul_f32 v[192:193], v[86:87], s[100:101] op_sel_hi:[1,0]
	v_pk_mul_f32 v[194:195], v[88:89], s[100:101] op_sel_hi:[1,0]
	v_exp_f32_e32 v188, v188
	v_exp_f32_e32 v189, v189
	v_exp_f32_e32 v190, v190
	v_exp_f32_e32 v191, v191
	v_exp_f32_e32 v192, v192
	v_exp_f32_e32 v193, v193
	v_exp_f32_e32 v194, v194
	v_exp_f32_e32 v195, v195
	v_pk_add_f32 v[204:205], v[204:205], 1.0 op_sel_hi:[1,0]
	v_pk_add_f32 v[206:207], v[206:207], 1.0 op_sel_hi:[1,0]
	v_pk_add_f32 v[208:209], v[208:209], 1.0 op_sel_hi:[1,0]
	v_pk_add_f32 v[210:211], v[210:211], 1.0 op_sel_hi:[1,0]
	v_rcp_f32_e32 v204, v204
	v_rcp_f32_e32 v205, v205
	v_rcp_f32_e32 v206, v206
	v_rcp_f32_e32 v207, v207
	v_rcp_f32_e32 v208, v208
	v_rcp_f32_e32 v209, v209
	v_rcp_f32_e32 v210, v210
	v_rcp_f32_e32 v211, v211
	v_pk_mul_f32 v[204:205], v[110:111], v[204:205]
	v_pk_mul_f32 v[206:207], v[112:113], v[206:207]
	v_pk_mul_f32 v[208:209], v[102:103], v[208:209]
	v_pk_mul_f32 v[210:211], v[104:105], v[210:211]
	v_pk_mul_f32 v[106:107], v[106:107], v[204:205]
	v_pk_mul_f32 v[108:109], v[108:109], v[206:207]
	v_pk_mul_f32 v[98:99], v[98:99], v[208:209]
	v_pk_mul_f32 v[100:101], v[100:101], v[210:211]
	v_cvt_pk_bf16_f32 v200, v106, v107
	v_cvt_pk_bf16_f32 v201, v108, v109
	v_cvt_pk_bf16_f32 v202, v98, v99
	v_cvt_pk_bf16_f32 v203, v100, v101
	global_store_dwordx4 v[162:163], v[200:203], off sc1
	v_pk_mul_f32 v[204:205], v[78:79], s[100:101] op_sel_hi:[1,0]
	v_pk_mul_f32 v[206:207], v[80:81], s[100:101] op_sel_hi:[1,0]
	v_pk_mul_f32 v[208:209], v[70:71], s[100:101] op_sel_hi:[1,0]
	v_pk_mul_f32 v[210:211], v[72:73], s[100:101] op_sel_hi:[1,0]
	v_exp_f32_e32 v204, v204
	v_exp_f32_e32 v205, v205
	v_exp_f32_e32 v206, v206
	v_exp_f32_e32 v207, v207
	v_exp_f32_e32 v208, v208
	v_exp_f32_e32 v209, v209
	v_exp_f32_e32 v210, v210
	v_exp_f32_e32 v211, v211
	v_pk_add_f32 v[188:189], v[188:189], 1.0 op_sel_hi:[1,0]
; __device__ __forceinline__ unsigned cvt_pk_bf16(float lo, float hi) { unsigned r; asm volatile("v_cvt_pk_bf16_f32 %0, %1, %2" : "=v"(r) : "v"(lo), "v"(hi)); return r; }
; __device__ __forceinline__ float siluf_(float x) { return x * __builtin_amdgcn_rcpf(1.0f + __expf(-x)); }
;     __device__ __forceinline__ void operator()(const f32x4 (&acc)[2][2][4][2], const Unit& u, int wr, int wc, int fr, int fq) const {
;     ...
;         for (int ai = 0; ai < 2; ++ai)
; #pragma unroll
;             for (int m = 0; m < 4; ++m) { bf16_t* rowp = O + (size_t)(row0 + ai * HALF + m * 16) * DFF + col0;
;                 float r[8];
; #pragma unroll
;                 for (int n = 0; n < 2; ++n)
; #pragma unroll
;                     for (int j = 0; j < 4; ++j) r[n * 4 + j] = siluf_(acc[ai][0][m][n][j]) * acc[ai][1][m][n][j];
;                 u32x4 w; w.x = cvt_pk_bf16(r[0], r[1]); w.y = cvt_pk_bf16(r[2], r[3]); w.z = cvt_pk_bf16(r[4], r[5]); w.w = cvt_pk_bf16(r[6], r[7]);
;                 *(u32x4*)rowp = w; }
	v_pk_add_f32 v[190:191], v[190:191], 1.0 op_sel_hi:[1,0]
	v_pk_add_f32 v[192:193], v[192:193], 1.0 op_sel_hi:[1,0]
	v_pk_add_f32 v[194:195], v[194:195], 1.0 op_sel_hi:[1,0]
	v_rcp_f32_e32 v188, v188
	v_rcp_f32_e32 v189, v189
	v_rcp_f32_e32 v190, v190
	v_rcp_f32_e32 v191, v191
	v_rcp_f32_e32 v192, v192
	v_rcp_f32_e32 v193, v193
	v_rcp_f32_e32 v194, v194
	v_rcp_f32_e32 v195, v195
	v_pk_mul_f32 v[188:189], v[94:95], v[188:189]
	v_pk_mul_f32 v[190:191], v[96:97], v[190:191]
	v_pk_mul_f32 v[192:193], v[86:87], v[192:193]
	v_pk_mul_f32 v[194:195], v[88:89], v[194:195]
	v_pk_mul_f32 v[90:91], v[90:91], v[188:189]
	v_pk_mul_f32 v[92:93], v[92:93], v[190:191]
	v_pk_mul_f32 v[82:83], v[82:83], v[192:193]
	v_pk_mul_f32 v[84:85], v[84:85], v[194:195]
	v_cvt_pk_bf16_f32 v196, v90, v91
	v_cvt_pk_bf16_f32 v197, v92, v93
	v_cvt_pk_bf16_f32 v198, v82, v83
	v_cvt_pk_bf16_f32 v199, v84, v85
	global_store_dwordx4 v[164:165], v[196:199], off sc1
	v_pk_mul_f32 v[188:189], v[62:63], s[100:101] op_sel_hi:[1,0]
	v_pk_mul_f32 v[190:191], v[64:65], s[100:101] op_sel_hi:[1,0]
	v_pk_mul_f32 v[192:193], v[54:55], s[100:101] op_sel_hi:[1,0]
	v_pk_mul_f32 v[194:195], v[56:57], s[100:101] op_sel_hi:[1,0]
	v_exp_f32_e32 v188, v188
	v_exp_f32_e32 v189, v189
	v_exp_f32_e32 v190, v190
	v_exp_f32_e32 v191, v191
	v_exp_f32_e32 v192, v192
	v_exp_f32_e32 v193, v193
	v_exp_f32_e32 v194, v194
	v_exp_f32_e32 v195, v195
	v_pk_add_f32 v[204:205], v[204:205], 1.0 op_sel_hi:[1,0]
	v_pk_add_f32 v[206:207], v[206:207], 1.0 op_sel_hi:[1,0]
	v_pk_add_f32 v[208:209], v[208:209], 1.0 op_sel_hi:[1,0]
	v_pk_add_f32 v[210:211], v[210:211], 1.0 op_sel_hi:[1,0]
	v_rcp_f32_e32 v204, v204
	v_rcp_f32_e32 v205, v205
	v_rcp_f32_e32 v206, v206
	v_rcp_f32_e32 v207, v207
	v_rcp_f32_e32 v208, v208
	v_rcp_f32_e32 v209, v209
	v_rcp_f32_e32 v210, v210
	v_rcp_f32_e32 v211, v211
	v_pk_mul_f32 v[204:205], v[78:79], v[204:205]
	v_pk_mul_f32 v[206:207], v[80:81], v[206:207]
	v_pk_mul_f32 v[208:209], v[70:71], v[208:209]
	v_pk_mul_f32 v[210:211], v[72:73], v[210:211]
	v_pk_mul_f32 v[74:75], v[74:75], v[204:205]
	v_pk_mul_f32 v[76:77], v[76:77], v[206:207]
	v_pk_mul_f32 v[66:67], v[66:67], v[208:209]
	v_pk_mul_f32 v[68:69], v[68:69], v[210:211]
	v_cvt_pk_bf16_f32 v200, v74, v75
	v_cvt_pk_bf16_f32 v201, v76, v77
	v_cvt_pk_bf16_f32 v202, v66, v67
	v_cvt_pk_bf16_f32 v203, v68, v69
	global_store_dwordx4 v[176:177], v[200:203], off sc1
	v_pk_mul_f32 v[204:205], v[46:47], s[100:101] op_sel_hi:[1,0]
	v_pk_mul_f32 v[206:207], v[48:49], s[100:101] op_sel_hi:[1,0]
	v_pk_mul_f32 v[208:209], v[38:39], s[100:101] op_sel_hi:[1,0]
	v_pk_mul_f32 v[210:211], v[40:41], s[100:101] op_sel_hi:[1,0]
	v_exp_f32_e32 v204, v204
	v_exp_f32_e32 v205, v205
	v_exp_f32_e32 v206, v206
	v_exp_f32_e32 v207, v207
	v_exp_f32_e32 v208, v208
	v_exp_f32_e32 v209, v209
	v_exp_f32_e32 v210, v210
	v_exp_f32_e32 v211, v211
	v_pk_add_f32 v[188:189], v[188:189], 1.0 op_sel_hi:[1,0]
	v_pk_add_f32 v[190:191], v[190:191], 1.0 op_sel_hi:[1,0]
	v_pk_add_f32 v[192:193], v[192:193], 1.0 op_sel_hi:[1,0]
	v_pk_add_f32 v[194:195], v[194:195], 1.0 op_sel_hi:[1,0]
	v_rcp_f32_e32 v188, v188
	v_rcp_f32_e32 v189, v189
	v_rcp_f32_e32 v190, v190
	v_rcp_f32_e32 v191, v191
	v_rcp_f32_e32 v192, v192
	v_rcp_f32_e32 v193, v193
	v_rcp_f32_e32 v194, v194
	v_rcp_f32_e32 v195, v195
	v_pk_mul_f32 v[188:189], v[62:63], v[188:189]
	v_pk_mul_f32 v[190:191], v[64:65], v[190:191]
	v_pk_mul_f32 v[192:193], v[54:55], v[192:193]
	v_pk_mul_f32 v[194:195], v[56:57], v[194:195]
	v_pk_mul_f32 v[58:59], v[58:59], v[188:189]
	v_pk_mul_f32 v[60:61], v[60:61], v[190:191]
	v_pk_mul_f32 v[50:51], v[50:51], v[192:193]
	v_pk_mul_f32 v[52:53], v[52:53], v[194:195]
	v_cvt_pk_bf16_f32 v196, v58, v59
	v_cvt_pk_bf16_f32 v197, v60, v61
	v_cvt_pk_bf16_f32 v198, v50, v51
	v_cvt_pk_bf16_f32 v199, v52, v53
	global_store_dwordx4 v[178:179], v[196:199], off sc1
	v_pk_mul_f32 v[188:189], v[28:29], s[100:101] op_sel_hi:[1,0]
; __device__ __forceinline__ unsigned cvt_pk_bf16(float lo, float hi) { unsigned r; asm volatile("v_cvt_pk_bf16_f32 %0, %1, %2" : "=v"(r) : "v"(lo), "v"(hi)); return r; }
; __device__ __forceinline__ float siluf_(float x) { return x * __builtin_amdgcn_rcpf(1.0f + __expf(-x)); }
; #define PG8_BAR __builtin_amdgcn_s_barrier()
; template <bool CHAIN, class Epi, class Sched>
; __device__ __forceinline__ void gemm_phase(LAS unsigned char* lds, const int tid, const int K, const int lda, const int ldb, const Sched& S, const Epi& E) {
;     ...
;         if (!has_next) break;
; #pragma unroll
;         for (int a = 0; a < 2; ++a)
; #pragma unroll
;             for (int b = 0; b < 2; ++b)
; #pragma unroll
;                 for (int m = 0; m < 4; ++m)
; #pragma unroll
;                     for (int n = 0; n < 2; ++n) acc[a][b][m][n] = (f32x4){0.f, 0.f, 0.f, 0.f};
;         cur = nxt; ++ui;
;         if (wr == 1) PG8_BAR;
;     __device__ __forceinline__ void operator()(const f32x4 (&acc)[2][2][4][2], const Unit& u, int wr, int wc, int fr, int fq) const {
;     ...
;         for (int ai = 0; ai < 2; ++ai)
; #pragma unroll
;             for (int m = 0; m < 4; ++m) { bf16_t* rowp = O + (size_t)(row0 + ai * HALF + m * 16) * DFF + col0;
;                 float r[8];
; #pragma unroll
;                 for (int n = 0; n < 2; ++n)
; #pragma unroll
;                     for (int j = 0; j < 4; ++j) r[n * 4 + j] = siluf_(acc[ai][0][m][n][j]) * acc[ai][1][m][n][j];
;                 u32x4 w; w.x = cvt_pk_bf16(r[0], r[1]); w.y = cvt_pk_bf16(r[2], r[3]); w.z = cvt_pk_bf16(r[4], r[5]); w.w = cvt_pk_bf16(r[6], r[7]);
;                 *(u32x4*)rowp = w; }
	v_pk_mul_f32 v[190:191], v[30:31], s[100:101] op_sel_hi:[1,0]
	v_pk_mul_f32 v[192:193], v[20:21], s[100:101] op_sel_hi:[1,0]
	v_pk_mul_f32 v[194:195], v[22:23], s[100:101] op_sel_hi:[1,0]
	v_exp_f32_e32 v188, v188
	v_exp_f32_e32 v189, v189
	v_exp_f32_e32 v190, v190
	v_exp_f32_e32 v191, v191
	v_exp_f32_e32 v192, v192
	v_exp_f32_e32 v193, v193
	v_exp_f32_e32 v194, v194
	v_exp_f32_e32 v195, v195
	v_pk_add_f32 v[204:205], v[204:205], 1.0 op_sel_hi:[1,0]
	v_pk_add_f32 v[206:207], v[206:207], 1.0 op_sel_hi:[1,0]
	v_pk_add_f32 v[208:209], v[208:209], 1.0 op_sel_hi:[1,0]
	v_pk_add_f32 v[210:211], v[210:211], 1.0 op_sel_hi:[1,0]
	v_rcp_f32_e32 v204, v204
	v_rcp_f32_e32 v205, v205
	v_rcp_f32_e32 v206, v206
	v_rcp_f32_e32 v207, v207
	v_rcp_f32_e32 v208, v208
	v_rcp_f32_e32 v209, v209
	v_rcp_f32_e32 v210, v210
	v_rcp_f32_e32 v211, v211
	v_pk_mul_f32 v[204:205], v[46:47], v[204:205]
	v_pk_mul_f32 v[206:207], v[48:49], v[206:207]
	v_pk_mul_f32 v[208:209], v[38:39], v[208:209]
	v_pk_mul_f32 v[210:211], v[40:41], v[210:211]
	v_pk_mul_f32 v[42:43], v[42:43], v[204:205]
	v_pk_mul_f32 v[44:45], v[44:45], v[206:207]
	v_pk_mul_f32 v[34:35], v[34:35], v[208:209]
	v_pk_mul_f32 v[36:37], v[36:37], v[210:211]
	v_cvt_pk_bf16_f32 v200, v42, v43
	v_cvt_pk_bf16_f32 v201, v44, v45
	v_cvt_pk_bf16_f32 v202, v34, v35
	v_cvt_pk_bf16_f32 v203, v36, v37
	global_store_dwordx4 v[180:181], v[200:203], off sc1
	v_pk_mul_f32 v[204:205], v[12:13], s[100:101] op_sel_hi:[1,0]
	v_pk_mul_f32 v[206:207], v[14:15], s[100:101] op_sel_hi:[1,0]
	v_pk_mul_f32 v[208:209], v[4:5], s[100:101] op_sel_hi:[1,0]
	v_pk_mul_f32 v[210:211], v[6:7], s[100:101] op_sel_hi:[1,0]
	v_exp_f32_e32 v204, v204
	v_exp_f32_e32 v205, v205
	v_exp_f32_e32 v206, v206
	v_exp_f32_e32 v207, v207
	v_exp_f32_e32 v208, v208
	v_exp_f32_e32 v209, v209
	v_exp_f32_e32 v210, v210
	v_exp_f32_e32 v211, v211
	v_pk_add_f32 v[188:189], v[188:189], 1.0 op_sel_hi:[1,0]
	v_pk_add_f32 v[190:191], v[190:191], 1.0 op_sel_hi:[1,0]
	v_pk_add_f32 v[192:193], v[192:193], 1.0 op_sel_hi:[1,0]
	v_pk_add_f32 v[194:195], v[194:195], 1.0 op_sel_hi:[1,0]
	v_rcp_f32_e32 v188, v188
	v_rcp_f32_e32 v189, v189
	v_rcp_f32_e32 v190, v190
	v_rcp_f32_e32 v191, v191
	v_rcp_f32_e32 v192, v192
	v_rcp_f32_e32 v193, v193
	v_rcp_f32_e32 v194, v194
	v_rcp_f32_e32 v195, v195
	v_pk_mul_f32 v[188:189], v[28:29], v[188:189]
	v_pk_mul_f32 v[190:191], v[30:31], v[190:191]
	v_pk_mul_f32 v[192:193], v[20:21], v[192:193]
	v_pk_mul_f32 v[194:195], v[22:23], v[194:195]
	v_pk_mul_f32 v[24:25], v[24:25], v[188:189]
	v_pk_mul_f32 v[26:27], v[26:27], v[190:191]
	v_pk_mul_f32 v[16:17], v[16:17], v[192:193]
	v_pk_mul_f32 v[18:19], v[18:19], v[194:195]
	v_cvt_pk_bf16_f32 v196, v24, v25
	v_cvt_pk_bf16_f32 v197, v26, v27
	v_cvt_pk_bf16_f32 v198, v16, v17
	v_cvt_pk_bf16_f32 v199, v18, v19
	global_store_dwordx4 v[182:183], v[196:199], off sc1
	v_pk_add_f32 v[204:205], v[204:205], 1.0 op_sel_hi:[1,0]
	v_pk_add_f32 v[206:207], v[206:207], 1.0 op_sel_hi:[1,0]
	v_pk_add_f32 v[208:209], v[208:209], 1.0 op_sel_hi:[1,0]
	v_pk_add_f32 v[210:211], v[210:211], 1.0 op_sel_hi:[1,0]
	v_rcp_f32_e32 v204, v204
	v_rcp_f32_e32 v205, v205
	v_rcp_f32_e32 v206, v206
	v_rcp_f32_e32 v207, v207
	v_rcp_f32_e32 v208, v208
	v_rcp_f32_e32 v209, v209
	v_rcp_f32_e32 v210, v210
	v_rcp_f32_e32 v211, v211
	v_pk_mul_f32 v[204:205], v[12:13], v[204:205]
	v_pk_mul_f32 v[206:207], v[14:15], v[206:207]
	v_pk_mul_f32 v[208:209], v[4:5], v[208:209]
	v_pk_mul_f32 v[210:211], v[6:7], v[210:211]
	v_pk_mul_f32 v[8:9], v[8:9], v[204:205]
	v_pk_mul_f32 v[10:11], v[10:11], v[206:207]
	v_pk_mul_f32 v[0:1], v[0:1], v[208:209]
	v_pk_mul_f32 v[2:3], v[2:3], v[210:211]
	v_cvt_pk_bf16_f32 v200, v8, v9
	v_cvt_pk_bf16_f32 v201, v10, v11
	v_cvt_pk_bf16_f32 v202, v0, v1
	v_cvt_pk_bf16_f32 v203, v2, v3
	global_store_dwordx4 v[184:185], v[200:203], off sc1
	s_andn2_b64 vcc, exec, s[40:41]
	s_cbranch_vccnz .LBB0_198
	s_andn2_b64 vcc, exec, s[20:21]
	s_cbranch_vccnz .LBB0_197
	s_barrier
	s_branch .LBB0_197
